# static setprio 1 for waves 4-7 also over the RG-LRU recurrence region (lever 4), on top of the attention static-priority version
# speedup vs baseline: 1.0066x; 1.0066x over previous
; __device__ __forceinline__ void lru_issue_x(const Frame& F, const bf16* XR, int b, int hh, int chunk) {
;     const int lane = F.lane, w = F.wave, g = lane >> 4, ql = lane & 15;
; #pragma unroll
;     for (int i = 0; i < 5; ++i) { const int rg = w + 8 * i;
;         if (rg < 33) { const int r = 4 * rg + g; int tok = chunk * 128 - 3 + r; tok = tok < 0 ? 0 : (tok > SEQ - 1 ? SEQ - 1 : tok);
;             const size_t go = ((size_t)(b * SEQ + tok) * 2048 + hh * 128 + ((ql ^ (r & 15)) << 3)) * 2;
;             __builtin_amdgcn_global_load_lds((const unsigned*)((const char*)XR + go), (LAS unsigned*)(F.lds + LRU_XBUF + (chunk & 1) * LRU_XBUF_STRIDE + rg * 1024), 16, 0, 0); } }
; }
; __device__ __forceinline__ void lru_item(const Frame& F, const bf16* XR, bf16* XGYL, const float* conv_w, const float* conv_b, const float* wa, const float* ba, const float* wx, const float* bx, const float* lam, int b, int hh, int j2) {
;     const int lane = F.lane, w = F.wave, g = lane >> 4, tl = lane & 15;
;     LAS float* tab = (LAS float*)F.lds;
;     LAS float* ctab = (LAS float*)(F.lds + LRU_CTAB);
;     LAS float* tot = (LAS float*)(F.lds + LRU_TOT);
;     LAS unsigned char* wfl = F.lds + LRU_WFL;
;     __syncthreads();
;     for (int i = F.tid; i < 640; i += NWAVES * 64) { const int k = i >> 7, c = i & 127; tab[i] = (k < 4) ? conv_w[k * 2048 + hh * 128 + c] : conv_b[hh * 128 + c]; }
;     if (F.tid < 192) { const int k = F.tid >> 6, c = F.tid & 63, ch = hh * 128 + 64 * j2 + c; ctab[F.tid] = (k == 0) ? ba[ch] : (k == 1 ? bx[ch] : 8.0f * log1pf(__expf(-lam[ch]))); }
; #pragma unroll
;     for (int ff = 0; ff < 4; ++ff) { const int fi = 4 * w + ff, T = fi >> 2, ks = fi & 3;
;         const float* p = ((T < 4) ? wa : wx) + (size_t)hh * 16384 + 64 * j2 + 32 * ((T >> 1) & 1) + 8 * (tl >> 2) + 4 * (T & 1) + (tl & 3) + (size_t)(32 * ks + 8 * g) * 128; v4u u4;
;         u4.x = pk2(p[0], p[128]); u4.y = pk2(p[256], p[384]); u4.z = pk2(p[512], p[640]); u4.w = pk2(p[768], p[896]);
;         *(LAS v4u*)(wfl + (fi * 64 + lane) * 16) = u4; }
;     const int chn = hh * 128 + 64 * j2 + 8 * g;
;     float hcl = 0.f;
;     __syncthreads();
;     lru_issue_x(F, XR, b, hh, 0);
;     asm volatile("s_waitcnt vmcnt(0)" ::: "memory"); WG_BAR();
;     for (int chunk = 0; chunk < 16; ++chunk) {
;         if (chunk < 15) lru_issue_x(F, XR, b, hh, chunk + 1);
.LBB0_315:
	v_writelane_b32 v234, s74, 41
	s_andn2_b64 vcc, exec, s[0:1]
	s_nop 0
	v_writelane_b32 v234, s75, 42
	v_writelane_b32 v234, s78, 43
	s_nop 1
	v_writelane_b32 v234, s79, 44
	v_writelane_b32 v234, s80, 45
	s_nop 1
	v_writelane_b32 v234, s81, 46
	v_writelane_b32 v234, s93, 47
	v_writelane_b32 v234, s92, 48
	v_writelane_b32 v234, s83, 49
	s_cbranch_vccnz .LBB0_421
	v_readfirstlane_b32 s2, v157
	s_lshr_b32 s2, s2, 8
	s_cmp_eq_u32 s2, 1
	s_cbranch_scc0 .Lprio1_done
	s_setprio 1
.Lprio1_done:
	s_movk_i32 s2, 0xc0
	v_and_b32_e32 v0, 0xc0, v157
	v_cmp_gt_u32_e64 s[58:59], s2, v157
	v_cmp_ne_u32_e64 s[2:3], 64, v0
	s_add_u32 s56, s88, 0x12000000
	s_addc_u32 s57, s89, 0
	v_writelane_b32 v234, s2, 50
	s_cmpk_lt_u32 s83, 0x100
	v_lshrrev_b32_e32 v81, 4, v156
	v_writelane_b32 v234, s3, 51
	v_bitop3_b32 v3, v81, v157, 15 bitop3:0x78
	v_readlane_b32 s8, v234, 5
	v_readlane_b32 s18, v234, 15
	v_readlane_b32 s19, v234, 16
	v_readlane_b32 s22, v234, 19
	v_readlane_b32 s23, v234, 20
	s_cselect_b32 s61, s19, s23
	s_cselect_b32 s64, s18, s22
	s_lshl_b32 s3, s92, 2
	s_lshl_b32 s2, s92, 4
	s_lshl_b32 s8, s92, 12
	v_or_b32_e32 v109, s3, v81
	s_and_b32 s6, s2, 32
	s_and_b32 s7, s3, 4
	s_add_i32 s65, s8, 0
	v_max_i32_e32 v1, 3, v109
	s_cmpk_lt_u32 s83, 0x840
	v_add_u32_e32 v1, -3, v1
	s_cselect_b64 s[62:63], -1, 0
	v_min_u32_e32 v110, 0x7ff, v1
	v_bitop3_b32 v1, s3, v157, v81 bitop3:0x36
	s_lshl_b32 s3, s92, 10
	s_add_i32 s60, s3, 0
	s_cmpk_lt_u32 s83, 0x640
	s_cselect_b64 s[66:67], -1, 0
	s_add_i32 s3, s92, 8
	v_lshlrev_b32_e32 v1, 3, v1
	s_lshl_b32 s8, s3, 2
	v_and_b32_e32 v78, 0x78, v1
	v_or_b32_e32 v1, s8, v81
	s_lshl_b32 s3, s3, 10
	v_max_i32_e32 v1, 3, v1
	s_add_i32 s68, s3, 0
	v_add_u32_e32 v1, -3, v1
	s_cmpk_lt_u32 s83, 0x440
	v_min_u32_e32 v111, 0x7ff, v1
	v_bitop3_b32 v1, s8, v157, v81 bitop3:0x36
	s_cselect_b64 s[74:75], -1, 0
	s_add_i32 s3, s92, 16
	v_lshlrev_b32_e32 v1, 3, v1
	s_lshl_b32 s8, s3, 2
	v_and_b32_e32 v80, 0x78, v1
	v_or_b32_e32 v1, s8, v81
	s_lshl_b32 s3, s3, 10
	v_lshlrev_b32_e32 v116, 4, v3
	v_add_u32_e32 v3, 1, v157
	v_max_i32_e32 v1, 3, v1
	s_add_i32 s69, s3, 0
	v_and_b32_e32 v4, 15, v3
	v_bitop3_b32 v3, v3, v81, 15 bitop3:0x6c
	v_add_u32_e32 v1, -3, v1
	s_cmpk_lt_u32 s83, 0x240
	v_lshlrev_b32_e32 v117, 4, v3
	v_add_u32_e32 v3, 2, v157
	v_min_u32_e32 v112, 0x7ff, v1
	v_bitop3_b32 v1, s8, v157, v81 bitop3:0x36
	s_cselect_b64 s[76:77], -1, 0
	s_add_i32 s3, s92, 24
	v_and_b32_e32 v5, 15, v3
	v_bitop3_b32 v3, v3, v81, 15 bitop3:0x6c
	v_lshlrev_b32_e32 v1, 3, v1
	s_lshl_b32 s8, s3, 2
	v_lshlrev_b32_e32 v118, 4, v3
	v_add_u32_e32 v3, 3, v157
	v_and_b32_e32 v79, 15, v157
	v_and_b32_e32 v82, 0x78, v1
	v_or_b32_e32 v1, s8, v81
	s_lshl_b32 s3, s3, 10
	v_and_b32_e32 v6, 15, v3
	v_bitop3_b32 v3, v3, v81, 15 bitop3:0x6c
	v_max_i32_e32 v1, 3, v1
	s_add_i32 s70, s3, 0
	v_lshlrev_b32_e32 v119, 4, v3
	v_bitop3_b32 v3, v81, v79, 4 bitop3:0x36
	v_readlane_b32 s9, v234, 6
	v_add_u32_e32 v1, -3, v1
	s_cmp_lt_u32 s83, 64
	v_lshlrev_b32_e32 v120, 4, v3
	v_bitop3_b32 v3, v81, v4, 4 bitop3:0x36
	v_min_u32_e32 v113, 0x7ff, v1
	v_bitop3_b32 v1, s8, v157, v81 bitop3:0x36
	s_cselect_b64 s[8:9], -1, 0
	v_or_b32_e32 v88, s2, v79
	s_and_b32 s2, s83, 0x1fffffc0
	v_lshlrev_b32_e32 v121, 4, v3
	v_bitop3_b32 v3, v81, v5, 4 bitop3:0x36
	v_readlane_b32 s16, v234, 13
	v_readlane_b32 s17, v234, 14
	v_lshlrev_b32_e32 v122, 4, v3
	v_bitop3_b32 v3, v81, v6, 4 bitop3:0x36
	s_cmp_eq_u32 s92, 1
	v_lshlrev_b32_e32 v123, 4, v3
	v_bitop3_b32 v3, v81, v79, 8 bitop3:0x36
	s_cselect_b64 s[16:17], -1, 0
	s_cmp_eq_u32 s92, 2
	v_readlane_b32 s20, v234, 17
	v_readlane_b32 s21, v234, 18
	v_lshlrev_b32_e32 v124, 4, v3
	v_bitop3_b32 v3, v81, v4, 8 bitop3:0x36
	s_cselect_b64 s[18:19], -1, 0
	s_cmp_eq_u32 s92, 3
	v_lshlrev_b32_e32 v1, 3, v1
	v_lshlrev_b32_e32 v125, 4, v3
	v_bitop3_b32 v3, v81, v5, 8 bitop3:0x36
	s_cselect_b64 s[20:21], -1, 0
	s_cmp_eq_u32 s92, 4
	v_and_b32_e32 v84, 0x78, v1
	v_xor_b32_e32 v1, v81, v157
	v_lshlrev_b32_e32 v126, 4, v3
	v_bitop3_b32 v3, v81, v6, 8 bitop3:0x36
	s_cselect_b64 s[22:23], -1, 0
	s_cmp_eq_u32 s92, 5
	v_mov_b32_e32 v69, 0
	v_lshlrev_b32_e32 v1, 3, v1
	v_lshlrev_b32_e32 v127, 4, v3
	v_bitop3_b32 v3, v81, v79, 12 bitop3:0x36
	s_cselect_b64 s[24:25], -1, 0
	s_cmp_eq_u32 s92, 6
	v_and_b32_e32 v86, 0x78, v1
	v_and_or_b32 v1, v157, 48, s2
	v_lshlrev_b32_e32 v128, 4, v3
	v_bitop3_b32 v3, v81, v4, 12 bitop3:0x36
	s_cselect_b64 s[26:27], -1, 0
	s_cmp_eq_u32 s92, 7
	v_mov_b32_e32 v89, v69
	v_and_b32_e32 v83, 0x7f, v157
	v_lshlrev_b32_e32 v0, 1, v157
	v_lshlrev_b32_e32 v129, 4, v3
	v_bitop3_b32 v3, v81, v5, 12 bitop3:0x36
	v_lshlrev_b32_e32 v132, 3, v1
	s_cselect_b64 s[28:29], -1, 0
	v_lshlrev_b32_e32 v1, 4, v157
	s_movk_i32 s2, 0x3800
	v_lshlrev_b64 v[4:5], 13, v[88:89]
	s_bitcmp1_b32 s93, 0
	s_movk_i32 s0, 0x280
	v_readlane_b32 s10, v234, 7
	v_readlane_b32 s11, v234, 8
	v_readlane_b32 s12, v234, 9
	v_readlane_b32 s13, v234, 10
	v_readlane_b32 s14, v234, 11
	v_readlane_b32 s15, v234, 12
	v_and_b32_e32 v0, 24, v0
	v_and_b32_e32 v2, 3, v157
	v_lshlrev_b32_e32 v70, 12, v81
	v_lshlrev_b32_e32 v130, 4, v3
	v_bitop3_b32 v3, v81, v6, 12 bitop3:0x36
	v_and_or_b32 v135, v1, s2, v83
	v_lshl_add_u64 v[4:5], s[86:87], 0, v[4:5]
	s_mov_b64 s[2:3], 0x1040
	s_cselect_b64 s[80:81], -1, 0
	s_bitcmp1_b32 s33, 0
	v_cmp_gt_u32_e64 s[0:1], s0, v157
	v_cmp_lt_u32_e64 s[4:5], 63, v157
	s_mov_b32 s73, 0
	v_lshl_add_u32 v85, v157, 2, 0
	v_lshlrev_b32_e32 v87, 3, v81
	v_mov_b32_e32 v71, v69
	v_lshlrev_b32_e32 v108, 4, v156
	v_or_b32_e32 v72, 0x4000, v70
	v_mov_b32_e32 v73, v69
	v_or_b32_e32 v74, 0x8000, v70
	v_mov_b32_e32 v75, v69
	v_or_b32_e32 v76, 0xc000, v70
	v_mov_b32_e32 v77, v69
	v_add_u32_e32 v114, 0x7d, v81
	v_lshl_add_u32 v115, v81, 5, 0
	v_cmp_eq_u32_e64 s[10:11], 15, v79
	v_cmp_lt_u32_e64 s[12:13], 2, v88
	v_cmp_lt_u32_e64 s[14:15], 1, v88
	v_lshlrev_b32_e32 v131, 4, v3
	v_lshlrev_b32_e32 v133, 3, v156
	v_lshl_add_u32 v134, v88, 8, 0
	v_lshl_add_u64 v[90:91], v[4:5], 0, s[2:3]
	s_cselect_b64 s[96:97], -1, 0
	v_mov_b32_e32 v89, 0x3ecc95a3
	s_lshl_b32 s71, s6, 2
	v_lshlrev_b32_e32 v68, 2, v0
	s_lshl_b32 s72, s7, 2
	v_lshlrev_b32_e32 v92, 2, v2
	s_movk_i32 s78, 0x7fff
	s_mov_b32 s79, 0xffff0000
	s_add_i32 s82, s60, 0xb000
	s_add_i32 s83, 0, 0x13000
	s_mov_b32 s92, 0xbe99999a
	v_mov_b32_e32 v136, 0x3d2aaaab
	v_mov_b32_e32 v94, 0x3f317218
	v_mov_b32_e32 v137, 0x7f800000
	v_mov_b32_e32 v138, 0x7fc00000
	v_mov_b32_e32 v139, 0xff800000
	s_branch .LBB0_318

; __global__ void __launch_bounds__(NWAVES * 64, 2) mega(Args args) {
;     ...
;         for (int it = F.vcu; it < 256; it += F.G) lru_item(F, (const bf16*)(ws + WS_XR), XGR, args.in[3], args.in[4], args.in[5], args.in[6], args.in[7], args.in[8], args.in[9], it >> 5, (it >> 1) & 15, it & 1);
;     ...
;         { const DecP2 dec{XNL, (bf16*)(ws + WS_O3), (float*)(ws + WS_LSE2), (float*)(ws + WS_LSE3)};
.LBB0_420:
	s_setprio 0
	v_readlane_b32 s80, v234, 45
	v_readlane_b32 s74, v234, 41
	v_readlane_b32 s78, v234, 43
	v_readlane_b32 s81, v234, 46
	v_readlane_b32 s93, v234, 47
	v_readlane_b32 s92, v234, 48
	v_readlane_b32 s83, v234, 49
	v_readlane_b32 s75, v234, 42
	v_readlane_b32 s79, v234, 44
